# dropped the redundant cooperative-groups grid sync at kernel start (first XCD barrier census already waits for all posts)
# speedup vs baseline: 1.0729x; 1.0086x over previous
.LBB0_5:
	s_or_b64 exec, exec, s[0:1]
	s_load_dwordx2 s[0:1], s[4:5], 0x4
	s_waitcnt lgkmcnt(0)
	v_mov_b32_e32 v1, v194
	s_barrier
	s_lshl_b32 s76, s70, 3
	v_readfirstlane_b32 s4, v1
	s_ashr_i32 s4, s4, 6
	s_lshl_b32 s78, s71, 3
	s_add_i32 s18, s4, s76
	s_mov_b64 s[2:3], s[72:73]
	s_cmpk_gt_i32 s18, 0x34ff
	s_cbranch_scc1 .LBB0_74
	v_bfe_u32 v0, v1, 5, 1
	v_and_b32_e32 v6, 31, v1
	v_bfe_u32 v5, v1, 3, 3
	v_lshlrev_b32_e32 v1, 3, v1
	s_lshl_b32 s6, s4, 14
	v_and_b32_e32 v10, 56, v1
	s_add_i32 s4, s6, 0
	v_mul_u32_u24_e32 v1, 0x84, v10
	v_lshlrev_b32_e32 v3, 2, v5
	v_add3_u32 v28, s4, v1, v3
	v_mul_u32_u24_e32 v3, 0x84, v0
	v_lshlrev_b32_e32 v2, 2, v6
	v_mov_b32_e32 v7, 0
	v_or_b32_e32 v3, s6, v3
	v_add_u32_e32 v4, s4, v2
	s_movk_i32 s19, 0x84
	v_or_b32_e32 v29, 8, v5
	v_or_b32_e32 v30, 16, v5
	v_or_b32_e32 v31, 24, v5
	v_cmp_gt_u32_e64 s[4:5], 16, v6
	v_mov_b32_e32 v1, v0
	v_add3_u32 v32, v3, v2, 0
	v_mov_b32_e32 v3, v7
	v_or_b32_e32 v33, 14, v0
	v_or_b32_e32 v34, 12, v0
	v_or_b32_e32 v35, 10, v0
	v_or_b32_e32 v36, 8, v0
	v_or_b32_e32 v37, 6, v0
	v_or_b32_e32 v38, 4, v0
	v_or_b32_e32 v39, 2, v0
	v_mul_u32_u24_e32 v40, 0x2810, v0
	s_movk_i32 s20, 0x70
	v_lshlrev_b32_e32 v8, 2, v6
	s_mov_b32 s21, 0x2f00000
	s_movk_i32 s22, 0x1810
	s_mov_b64 s[6:7], 0x100000
	v_lshlrev_b32_e32 v10, 1, v10
	s_branch .LBB0_19
